# P1 K-loop: A[x][0] LDS-DMA stage moved from the 6-load segment to the next 2-load segment (4/4 balance), counted waits 8/6
# speedup vs baseline: 1.0041x; 1.0041x over previous
; #define PG8_STAGE(bufoff, gbase, voff) do { _Pragma("unroll") for (int _i = 0; _i < 2; ++_i) \
;         __builtin_amdgcn_global_load_lds((const unsigned*)((const char*)(gbase) + (voff)[_i]), (PG8_LAS unsigned*)(lds + (bufoff) + ldsw + _i * 8192), 16, 0, 0); } while (0)
; #define PG8_LDA(dst, b, h) do { _Pragma("unroll") for (int m = 0; m < 4; ++m) _Pragma("unroll") for (int k = 0; k < 2; ++k) dst[m][k] = *(const PG8_LAS bf16x8*)(lds + PG8_SA(b, h) + aoff + m * 2048 + k * 1024); } while (0)
; #define PG8_LDB(dst, b, h) do { _Pragma("unroll") for (int n = 0; n < 2; ++n) _Pragma("unroll") for (int k = 0; k < 2; ++k) dst[n][k] = *(const PG8_LAS bf16x8*)(lds + PG8_SB(b, h) + boff + n * 2048 + k * 1024); } while (0)
; #define PG8_MMA(ai, bj, At, Bt) do { __builtin_amdgcn_s_setprio(1); _Pragma("unroll") for (int m = 0; m < 4; ++m) _Pragma("unroll") for (int n = 0; n < 2; ++n) _Pragma("unroll") for (int k = 0; k < 2; ++k) \
;         acc[ai][bj][m][n] = __builtin_amdgcn_mfma_f32_16x16x32_bf16(Bt[n][k], At[m][k], acc[ai][bj][m][n], 0, 0, 0); __builtin_amdgcn_s_setprio(0); } while (0)
; #define PG8_WAIT_V(n) asm volatile("s_waitcnt vmcnt(" #n ")" ::: "memory")
; #define PG8_WAIT_L(n) asm volatile("s_waitcnt lgkmcnt(" #n ")" ::: "memory")
; #define PG8_BAR __builtin_amdgcn_s_barrier()
; #define PG8_SCHED __builtin_amdgcn_sched_barrier(0)
; template <class Epi, class Sched, bool ALIGN_EPI = false, bool SP2 = false>
; __device__ __forceinline__ void gemm_phase(PG8_LAS unsigned char* lds, const Gemm g, const Sched& S, const Epi& E) {
;     ...
;             const bool last = (t == nt - 2);
;             const char* a1 = cA + (size_t)(t + 1) * kstep;
;             const char* a2 = last ? nA : cA + (size_t)(t + 2) * kstep; const char* b2 = last ? nB : cB + (size_t)(t + 2) * kstep;
;             const char* a3 = a2 + kstep; const char* b3 = b2 + kstep;
;             if (last && has_next) S.a_ready(nxt);
;             if constexpr (SP2) {
;             PG8_LDB(B0, 0, 0); PG8_LDB(B1, 0, 1); PG8_SCHED; PG8_LDA(At, 0, 0); PG8_STAGE(PG8_SA(1, 1), a1 + hstep, voffA);
;             PG8_WAIT_V(8); PG8_WAIT_L(0); PG8_BAR; PG8_MMA(0, 0, At, B0); PG8_MMA(0, 1, At, B1); PG8_BAR; PG8_SCHED;
;             PG8_LDA(At, 0, 1); PG8_STAGE(PG8_SB(0, 0), b2, voffB); PG8_STAGE(PG8_SB(0, 1), b2 + hstep, voffB); PG8_STAGE(PG8_SA(0, 0), a2, voffA);
.LBB0_115:
	ds_read_b128 v[154:157], v150
	ds_read_b128 v[158:161], v150 offset:1024
	ds_read_b128 v[162:165], v150 offset:2048
	ds_read_b128 v[166:169], v150 offset:3072
	ds_read_b128 v[170:173], v151
	ds_read_b128 v[174:177], v151 offset:1024
	ds_read_b128 v[180:183], v151 offset:2048
	ds_read_b128 v[184:187], v151 offset:3072
	s_add_u32 s50, s48, 0x4000
	s_addc_u32 s51, s49, 0
	s_cmp_eq_u32 s76, 60
	s_cselect_b32 s74, s64, s50
	s_cselect_b32 s75, s25, s51
	s_cselect_b32 s72, s65, s68
	s_cselect_b32 s73, s19, s69
	s_sub_u32 s50, s48, 0x4000
	s_subb_u32 s51, s49, 0
	v_lshl_add_u64 v[224:225], s[50:51], 0, v[130:131]
	s_mov_b32 m0, s58
	s_nop 0
	global_load_lds_dwordx4 v[224:225], off
	v_lshl_add_u64 v[224:225], s[50:51], 0, v[134:135]
	s_mov_b32 m0, s59
	s_nop 0
	global_load_lds_dwordx4 v[224:225], off
	v_lshl_add_u64 v[224:225], s[48:49], 0, v[140:141]
	s_add_i32 m0, s28, 0xc000
	ds_read_b128 v[188:191], v152
	ds_read_b128 v[196:199], v152 offset:1024
	ds_read_b128 v[200:203], v152 offset:2048
	ds_read_b128 v[204:207], v152 offset:3072
	ds_read_b128 v[208:211], v152 offset:4096
	ds_read_b128 v[212:215], v152 offset:5120
	ds_read_b128 v[216:219], v152 offset:6144
	ds_read_b128 v[220:223], v152 offset:7168
	global_load_lds_dwordx4 v[224:225], off
	v_lshl_add_u64 v[224:225], s[48:49], 0, v[142:143]
	s_add_i32 m0, s28, 0xe000
	s_nop 0
	global_load_lds_dwordx4 v[224:225], off
	s_waitcnt vmcnt(8)
	s_waitcnt lgkmcnt(0)
	s_barrier
	s_setprio 1
	s_waitcnt lgkmcnt(0)
	v_mfma_f32_16x16x32_bf16 v[126:129], v[154:157], v[188:191], v[126:129]
	v_mfma_f32_16x16x32_bf16 v[118:121], v[162:165], v[188:191], v[118:121]
	v_mfma_f32_16x16x32_bf16 v[110:113], v[154:157], v[200:203], v[110:113]
	v_mfma_f32_16x16x32_bf16 v[102:105], v[162:165], v[200:203], v[102:105]
	v_mfma_f32_16x16x32_bf16 v[94:97], v[154:157], v[208:211], v[94:97]
	v_mfma_f32_16x16x32_bf16 v[86:89], v[162:165], v[208:211], v[86:89]
	v_mfma_f32_16x16x32_bf16 v[78:81], v[154:157], v[216:219], v[78:81]
	v_mfma_f32_16x16x32_bf16 v[70:73], v[162:165], v[216:219], v[70:73]
	v_mfma_f32_16x16x32_bf16 v[126:129], v[158:161], v[196:199], v[126:129]
	v_mfma_f32_16x16x32_bf16 v[118:121], v[166:169], v[196:199], v[118:121]
	v_mfma_f32_16x16x32_bf16 v[110:113], v[158:161], v[204:207], v[110:113]
	v_mfma_f32_16x16x32_bf16 v[102:105], v[166:169], v[204:207], v[102:105]
	v_mfma_f32_16x16x32_bf16 v[94:97], v[158:161], v[212:215], v[94:97]
	v_mfma_f32_16x16x32_bf16 v[86:89], v[166:169], v[212:215], v[86:89]
	v_mfma_f32_16x16x32_bf16 v[78:81], v[158:161], v[220:223], v[78:81]
	v_mfma_f32_16x16x32_bf16 v[70:73], v[166:169], v[220:223], v[70:73]
	s_setprio 0
	s_setprio 1
	v_mfma_f32_16x16x32_bf16 v[122:125], v[170:173], v[188:191], v[122:125]
	v_mfma_f32_16x16x32_bf16 v[114:117], v[180:183], v[188:191], v[114:117]
	v_mfma_f32_16x16x32_bf16 v[106:109], v[170:173], v[200:203], v[106:109]
	v_mfma_f32_16x16x32_bf16 v[98:101], v[180:183], v[200:203], v[98:101]
	v_mfma_f32_16x16x32_bf16 v[90:93], v[170:173], v[208:211], v[90:93]
	v_mfma_f32_16x16x32_bf16 v[82:85], v[180:183], v[208:211], v[82:85]
	v_mfma_f32_16x16x32_bf16 v[74:77], v[170:173], v[216:219], v[74:77]
	v_mfma_f32_16x16x32_bf16 v[66:69], v[180:183], v[216:219], v[66:69]
	v_mfma_f32_16x16x32_bf16 v[122:125], v[174:177], v[196:199], v[122:125]
	v_mfma_f32_16x16x32_bf16 v[114:117], v[184:187], v[196:199], v[114:117]
	v_mfma_f32_16x16x32_bf16 v[106:109], v[174:177], v[204:207], v[106:109]
	v_mfma_f32_16x16x32_bf16 v[98:101], v[184:187], v[204:207], v[98:101]
	v_mfma_f32_16x16x32_bf16 v[90:93], v[174:177], v[212:215], v[90:93]
	v_mfma_f32_16x16x32_bf16 v[82:85], v[184:187], v[212:215], v[82:85]
	v_mfma_f32_16x16x32_bf16 v[74:77], v[174:177], v[220:223], v[74:77]
	v_mfma_f32_16x16x32_bf16 v[66:69], v[184:187], v[220:223], v[66:69]
	s_setprio 0
	s_barrier
	s_add_i32 s77, s61, s3
	v_lshl_add_u64 v[224:225], s[72:73], 0, v[132:133]
	s_mov_b32 m0, s77
	ds_read_b128 v[188:191], v152 offset:16384
	ds_read_b128 v[196:199], v152 offset:17408
	ds_read_b128 v[200:203], v152 offset:18432
	ds_read_b128 v[204:207], v152 offset:19456
	ds_read_b128 v[208:211], v152 offset:20480
	ds_read_b128 v[212:215], v152 offset:21504
	ds_read_b128 v[216:219], v152 offset:22528
	ds_read_b128 v[220:223], v152 offset:23552
	global_load_lds_dwordx4 v[224:225], off
	s_add_i32 m0, s77, 0x2000
	s_add_u32 s78, s72, 0x4000
	v_lshl_add_u64 v[224:225], s[72:73], 0, v[136:137]
	s_addc_u32 s79, s73, 0
	s_add_i32 s77, s62, s3
	global_load_lds_dwordx4 v[224:225], off
	v_lshl_add_u64 v[224:225], s[78:79], 0, v[132:133]
	s_mov_b32 m0, s77
	s_nop 0
	global_load_lds_dwordx4 v[224:225], off
	v_lshl_add_u64 v[224:225], s[78:79], 0, v[136:137]
	s_add_i32 m0, s77, 0x2000
	s_nop 0
	global_load_lds_dwordx4 v[224:225], off
	s_waitcnt vmcnt(6)
	s_waitcnt lgkmcnt(0)
	s_barrier
; #define PG8_STAGE(bufoff, gbase, voff) do { _Pragma("unroll") for (int _i = 0; _i < 2; ++_i) \
;         __builtin_amdgcn_global_load_lds((const unsigned*)((const char*)(gbase) + (voff)[_i]), (PG8_LAS unsigned*)(lds + (bufoff) + ldsw + _i * 8192), 16, 0, 0); } while (0)
; #define PG8_LDA(dst, b, h) do { _Pragma("unroll") for (int m = 0; m < 4; ++m) _Pragma("unroll") for (int k = 0; k < 2; ++k) dst[m][k] = *(const PG8_LAS bf16x8*)(lds + PG8_SA(b, h) + aoff + m * 2048 + k * 1024); } while (0)
; #define PG8_LDB(dst, b, h) do { _Pragma("unroll") for (int n = 0; n < 2; ++n) _Pragma("unroll") for (int k = 0; k < 2; ++k) dst[n][k] = *(const PG8_LAS bf16x8*)(lds + PG8_SB(b, h) + boff + n * 2048 + k * 1024); } while (0)
; #define PG8_MMA(ai, bj, At, Bt) do { __builtin_amdgcn_s_setprio(1); _Pragma("unroll") for (int m = 0; m < 4; ++m) _Pragma("unroll") for (int n = 0; n < 2; ++n) _Pragma("unroll") for (int k = 0; k < 2; ++k) \
;         acc[ai][bj][m][n] = __builtin_amdgcn_mfma_f32_16x16x32_bf16(Bt[n][k], At[m][k], acc[ai][bj][m][n], 0, 0, 0); __builtin_amdgcn_s_setprio(0); } while (0)
; #define PG8_WAIT_V(n) asm volatile("s_waitcnt vmcnt(" #n ")" ::: "memory")
; #define PG8_WAIT_L(n) asm volatile("s_waitcnt lgkmcnt(" #n ")" ::: "memory")
; #define PG8_BAR __builtin_amdgcn_s_barrier()
; #define PG8_SCHED __builtin_amdgcn_sched_barrier(0)
; template <class Epi, class Sched, bool ALIGN_EPI = false, bool SP2 = false>
; __device__ __forceinline__ void gemm_phase(PG8_LAS unsigned char* lds, const Gemm g, const Sched& S, const Epi& E) {
;     ...
;             PG8_LDA(At, 0, 1); PG8_STAGE(PG8_SB(0, 0), b2, voffB); PG8_STAGE(PG8_SB(0, 1), b2 + hstep, voffB); PG8_STAGE(PG8_SA(0, 0), a2, voffA);
;             PG8_WAIT_V(8); PG8_WAIT_L(0); PG8_BAR; PG8_MMA(1, 0, At, B0); PG8_MMA(1, 1, At, B1); PG8_BAR; PG8_SCHED;
;             PG8_LDB(B0, 1, 0); PG8_LDB(B1, 1, 1); PG8_SCHED; PG8_LDA(At, 1, 0); PG8_STAGE(PG8_SA(0, 1), a2 + hstep, voffA);
	s_setprio 1
	s_waitcnt lgkmcnt(0)
	v_mfma_f32_16x16x32_bf16 v[62:65], v[154:157], v[188:191], v[62:65]
	v_mfma_f32_16x16x32_bf16 v[54:57], v[162:165], v[188:191], v[54:57]
	v_mfma_f32_16x16x32_bf16 v[46:49], v[154:157], v[200:203], v[46:49]
	v_mfma_f32_16x16x32_bf16 v[38:41], v[162:165], v[200:203], v[38:41]
	v_mfma_f32_16x16x32_bf16 v[30:33], v[154:157], v[208:211], v[30:33]
	v_mfma_f32_16x16x32_bf16 v[22:25], v[162:165], v[208:211], v[22:25]
	v_mfma_f32_16x16x32_bf16 v[14:17], v[154:157], v[216:219], v[14:17]
	v_mfma_f32_16x16x32_bf16 v[6:9], v[162:165], v[216:219], v[6:9]
	v_mfma_f32_16x16x32_bf16 v[62:65], v[158:161], v[196:199], v[62:65]
	v_mfma_f32_16x16x32_bf16 v[54:57], v[166:169], v[196:199], v[54:57]
	v_mfma_f32_16x16x32_bf16 v[46:49], v[158:161], v[204:207], v[46:49]
	v_mfma_f32_16x16x32_bf16 v[38:41], v[166:169], v[204:207], v[38:41]
	v_mfma_f32_16x16x32_bf16 v[30:33], v[158:161], v[212:215], v[30:33]
	v_mfma_f32_16x16x32_bf16 v[22:25], v[166:169], v[212:215], v[22:25]
	v_mfma_f32_16x16x32_bf16 v[14:17], v[158:161], v[220:223], v[14:17]
	v_mfma_f32_16x16x32_bf16 v[6:9], v[166:169], v[220:223], v[6:9]
	s_setprio 0
	s_setprio 1
	v_mfma_f32_16x16x32_bf16 v[58:61], v[170:173], v[188:191], v[58:61]
	v_mfma_f32_16x16x32_bf16 v[50:53], v[180:183], v[188:191], v[50:53]
	v_mfma_f32_16x16x32_bf16 v[42:45], v[170:173], v[200:203], v[42:45]
	v_mfma_f32_16x16x32_bf16 v[34:37], v[180:183], v[200:203], v[34:37]
	v_mfma_f32_16x16x32_bf16 v[26:29], v[170:173], v[208:211], v[26:29]
	v_mfma_f32_16x16x32_bf16 v[18:21], v[180:183], v[208:211], v[18:21]
	v_mfma_f32_16x16x32_bf16 v[10:13], v[170:173], v[216:219], v[10:13]
	v_mfma_f32_16x16x32_bf16 v[2:5], v[180:183], v[216:219], v[2:5]
	v_mfma_f32_16x16x32_bf16 v[58:61], v[174:177], v[196:199], v[58:61]
	v_mfma_f32_16x16x32_bf16 v[50:53], v[184:187], v[196:199], v[50:53]
	v_mfma_f32_16x16x32_bf16 v[42:45], v[174:177], v[204:207], v[42:45]
	v_mfma_f32_16x16x32_bf16 v[34:37], v[184:187], v[204:207], v[34:37]
	v_mfma_f32_16x16x32_bf16 v[26:29], v[174:177], v[212:215], v[26:29]
	v_mfma_f32_16x16x32_bf16 v[18:21], v[184:187], v[212:215], v[18:21]
	v_mfma_f32_16x16x32_bf16 v[10:13], v[174:177], v[220:223], v[10:13]
	v_mfma_f32_16x16x32_bf16 v[2:5], v[184:187], v[220:223], v[2:5]
	s_setprio 0
	s_barrier
	s_add_i32 s77, 0, 0x18000
	v_add_u32_e32 v138, s77, v148
	s_add_i32 s78, 0, 0x1c000
	ds_read_b128 v[154:157], v138
	ds_read_b128 v[158:161], v138 offset:1024
	ds_read_b128 v[162:165], v138 offset:2048
	ds_read_b128 v[166:169], v138 offset:3072
	v_add_u32_e32 v138, s78, v148
	ds_read_b128 v[170:173], v138
	ds_read_b128 v[174:177], v138 offset:1024
	ds_read_b128 v[180:183], v138 offset:2048
	ds_read_b128 v[184:187], v138 offset:3072
	v_lshl_add_u64 v[224:225], s[74:75], 0, v[130:131]
	s_mov_b32 m0, s28
	s_nop 0
	global_load_lds_dwordx4 v[224:225], off
	v_lshl_add_u64 v[224:225], s[74:75], 0, v[134:135]
	s_mov_b32 m0, s29
	s_nop 0
	global_load_lds_dwordx4 v[224:225], off
	s_add_u32 s74, s74, 0x4000
	s_addc_u32 s75, s75, 0
	s_mov_b32 m0, s30
	v_lshl_add_u64 v[224:225], s[74:75], 0, v[130:131]
	ds_read_b128 v[188:191], v152 offset:32768
	ds_read_b128 v[196:199], v152 offset:33792
	ds_read_b128 v[200:203], v152 offset:34816
	ds_read_b128 v[204:207], v152 offset:35840
	ds_read_b128 v[208:211], v152 offset:36864
	ds_read_b128 v[212:215], v152 offset:37888
	ds_read_b128 v[216:219], v152 offset:38912
	ds_read_b128 v[220:223], v152 offset:39936
	global_load_lds_dwordx4 v[224:225], off
	v_lshl_add_u64 v[224:225], s[74:75], 0, v[134:135]
	s_mov_b32 m0, s31
	s_nop 0
	global_load_lds_dwordx4 v[224:225], off
	s_waitcnt vmcnt(8)
	s_waitcnt lgkmcnt(0)
	s_barrier
; #define PG8_STAGE(bufoff, gbase, voff) do { _Pragma("unroll") for (int _i = 0; _i < 2; ++_i) \
;         __builtin_amdgcn_global_load_lds((const unsigned*)((const char*)(gbase) + (voff)[_i]), (PG8_LAS unsigned*)(lds + (bufoff) + ldsw + _i * 8192), 16, 0, 0); } while (0)
; #define PG8_LDA(dst, b, h) do { _Pragma("unroll") for (int m = 0; m < 4; ++m) _Pragma("unroll") for (int k = 0; k < 2; ++k) dst[m][k] = *(const PG8_LAS bf16x8*)(lds + PG8_SA(b, h) + aoff + m * 2048 + k * 1024); } while (0)
; #define PG8_MMA(ai, bj, At, Bt) do { __builtin_amdgcn_s_setprio(1); _Pragma("unroll") for (int m = 0; m < 4; ++m) _Pragma("unroll") for (int n = 0; n < 2; ++n) _Pragma("unroll") for (int k = 0; k < 2; ++k) \
;         acc[ai][bj][m][n] = __builtin_amdgcn_mfma_f32_16x16x32_bf16(Bt[n][k], At[m][k], acc[ai][bj][m][n], 0, 0, 0); __builtin_amdgcn_s_setprio(0); } while (0)
; #define PG8_WAIT_V(n) asm volatile("s_waitcnt vmcnt(" #n ")" ::: "memory")
; #define PG8_WAIT_L(n) asm volatile("s_waitcnt lgkmcnt(" #n ")" ::: "memory")
; #define PG8_BAR __builtin_amdgcn_s_barrier()
; #define PG8_SCHED __builtin_amdgcn_sched_barrier(0)
; template <class Epi, class Sched, bool ALIGN_EPI = false, bool SP2 = false>
; __device__ __forceinline__ void gemm_phase(PG8_LAS unsigned char* lds, const Gemm g, const Sched& S, const Epi& E) {
;     ...
;             PG8_WAIT_V(8); PG8_WAIT_L(0); PG8_BAR; PG8_MMA(0, 0, At, B0); PG8_MMA(0, 1, At, B1); PG8_BAR; PG8_SCHED;
;             PG8_LDA(At, 1, 1); PG8_STAGE(PG8_SB(1, 0), b3, voffB); PG8_STAGE(PG8_SB(1, 1), b3 + hstep, voffB); PG8_STAGE(PG8_SA(1, 0), a3, voffA);
;             PG8_WAIT_V(8); PG8_WAIT_L(0); PG8_BAR; PG8_MMA(1, 0, At, B0); PG8_MMA(1, 1, At, B1); PG8_BAR; PG8_SCHED;
;     ...
;         if constexpr (ALIGN_EPI) { if (wr == 0) PG8_BAR; }
	s_setprio 1
	s_waitcnt lgkmcnt(0)
	v_mfma_f32_16x16x32_bf16 v[126:129], v[154:157], v[188:191], v[126:129]
	v_mfma_f32_16x16x32_bf16 v[118:121], v[162:165], v[188:191], v[118:121]
	v_mfma_f32_16x16x32_bf16 v[110:113], v[154:157], v[200:203], v[110:113]
	v_mfma_f32_16x16x32_bf16 v[102:105], v[162:165], v[200:203], v[102:105]
	v_mfma_f32_16x16x32_bf16 v[94:97], v[154:157], v[208:211], v[94:97]
	v_mfma_f32_16x16x32_bf16 v[86:89], v[162:165], v[208:211], v[86:89]
	v_mfma_f32_16x16x32_bf16 v[78:81], v[154:157], v[216:219], v[78:81]
	v_mfma_f32_16x16x32_bf16 v[70:73], v[162:165], v[216:219], v[70:73]
	v_mfma_f32_16x16x32_bf16 v[126:129], v[158:161], v[196:199], v[126:129]
	v_mfma_f32_16x16x32_bf16 v[118:121], v[166:169], v[196:199], v[118:121]
	v_mfma_f32_16x16x32_bf16 v[110:113], v[158:161], v[204:207], v[110:113]
	v_mfma_f32_16x16x32_bf16 v[102:105], v[166:169], v[204:207], v[102:105]
	v_mfma_f32_16x16x32_bf16 v[94:97], v[158:161], v[212:215], v[94:97]
	v_mfma_f32_16x16x32_bf16 v[86:89], v[166:169], v[212:215], v[86:89]
	v_mfma_f32_16x16x32_bf16 v[78:81], v[158:161], v[220:223], v[78:81]
	v_mfma_f32_16x16x32_bf16 v[70:73], v[166:169], v[220:223], v[70:73]
	s_setprio 0
	s_setprio 1
	v_mfma_f32_16x16x32_bf16 v[122:125], v[170:173], v[188:191], v[122:125]
	v_mfma_f32_16x16x32_bf16 v[114:117], v[180:183], v[188:191], v[114:117]
	v_mfma_f32_16x16x32_bf16 v[106:109], v[170:173], v[200:203], v[106:109]
	v_mfma_f32_16x16x32_bf16 v[98:101], v[180:183], v[200:203], v[98:101]
	v_mfma_f32_16x16x32_bf16 v[90:93], v[170:173], v[208:211], v[90:93]
	v_mfma_f32_16x16x32_bf16 v[82:85], v[180:183], v[208:211], v[82:85]
	v_mfma_f32_16x16x32_bf16 v[74:77], v[170:173], v[216:219], v[74:77]
	v_mfma_f32_16x16x32_bf16 v[66:69], v[180:183], v[216:219], v[66:69]
	v_mfma_f32_16x16x32_bf16 v[122:125], v[174:177], v[196:199], v[122:125]
	v_mfma_f32_16x16x32_bf16 v[114:117], v[184:187], v[196:199], v[114:117]
	v_mfma_f32_16x16x32_bf16 v[106:109], v[174:177], v[204:207], v[106:109]
	v_mfma_f32_16x16x32_bf16 v[98:101], v[184:187], v[204:207], v[98:101]
	v_mfma_f32_16x16x32_bf16 v[90:93], v[174:177], v[212:215], v[90:93]
	v_mfma_f32_16x16x32_bf16 v[82:85], v[184:187], v[212:215], v[82:85]
	v_mfma_f32_16x16x32_bf16 v[74:77], v[174:177], v[220:223], v[74:77]
	v_mfma_f32_16x16x32_bf16 v[66:69], v[184:187], v[220:223], v[66:69]
	s_setprio 0
	s_barrier
	s_add_u32 s74, s72, 0x8000
	s_addc_u32 s75, s73, 0
	s_add_i32 s77, s77, s3
	v_lshl_add_u64 v[224:225], s[74:75], 0, v[132:133]
	s_mov_b32 m0, s77
	ds_read_b128 v[188:191], v152 offset:49152
	ds_read_b128 v[196:199], v152 offset:50176
	ds_read_b128 v[200:203], v152 offset:51200
	ds_read_b128 v[204:207], v152 offset:52224
	ds_read_b128 v[208:211], v152 offset:53248
	ds_read_b128 v[212:215], v152 offset:54272
	ds_read_b128 v[216:219], v152 offset:55296
	ds_read_b128 v[220:223], v152 offset:56320
	global_load_lds_dwordx4 v[224:225], off
	s_add_i32 m0, s77, 0x2000
	s_add_u32 s72, s72, 0xc000
	v_lshl_add_u64 v[224:225], s[74:75], 0, v[136:137]
	s_addc_u32 s73, s73, 0
	s_add_i32 s74, s78, s3
	global_load_lds_dwordx4 v[224:225], off
	v_lshl_add_u64 v[224:225], s[72:73], 0, v[132:133]
	s_mov_b32 m0, s74
	s_nop 0
	global_load_lds_dwordx4 v[224:225], off
	v_lshl_add_u64 v[224:225], s[72:73], 0, v[136:137]
	s_add_i32 m0, s74, 0x2000
	s_nop 0
	global_load_lds_dwordx4 v[224:225], off
	s_waitcnt vmcnt(6)
	s_waitcnt lgkmcnt(0)
	s_barrier
	s_setprio 1
	s_waitcnt lgkmcnt(0)
	v_mfma_f32_16x16x32_bf16 v[62:65], v[154:157], v[188:191], v[62:65]
	v_mfma_f32_16x16x32_bf16 v[54:57], v[162:165], v[188:191], v[54:57]
	v_mfma_f32_16x16x32_bf16 v[46:49], v[154:157], v[200:203], v[46:49]
	v_mfma_f32_16x16x32_bf16 v[38:41], v[162:165], v[200:203], v[38:41]
	v_mfma_f32_16x16x32_bf16 v[30:33], v[154:157], v[208:211], v[30:33]
	v_mfma_f32_16x16x32_bf16 v[22:25], v[162:165], v[208:211], v[22:25]
	v_mfma_f32_16x16x32_bf16 v[14:17], v[154:157], v[216:219], v[14:17]
	v_mfma_f32_16x16x32_bf16 v[6:9], v[162:165], v[216:219], v[6:9]
	v_mfma_f32_16x16x32_bf16 v[62:65], v[158:161], v[196:199], v[62:65]
	v_mfma_f32_16x16x32_bf16 v[54:57], v[166:169], v[196:199], v[54:57]
	v_mfma_f32_16x16x32_bf16 v[46:49], v[158:161], v[204:207], v[46:49]
	v_mfma_f32_16x16x32_bf16 v[38:41], v[166:169], v[204:207], v[38:41]
	v_mfma_f32_16x16x32_bf16 v[30:33], v[158:161], v[212:215], v[30:33]
	v_mfma_f32_16x16x32_bf16 v[22:25], v[166:169], v[212:215], v[22:25]
	v_mfma_f32_16x16x32_bf16 v[14:17], v[158:161], v[220:223], v[14:17]
	v_mfma_f32_16x16x32_bf16 v[6:9], v[166:169], v[220:223], v[6:9]
	s_setprio 0
	s_setprio 1
	v_mfma_f32_16x16x32_bf16 v[58:61], v[170:173], v[188:191], v[58:61]
	v_mfma_f32_16x16x32_bf16 v[50:53], v[180:183], v[188:191], v[50:53]
	v_mfma_f32_16x16x32_bf16 v[42:45], v[170:173], v[200:203], v[42:45]
	v_mfma_f32_16x16x32_bf16 v[34:37], v[180:183], v[200:203], v[34:37]
	v_mfma_f32_16x16x32_bf16 v[26:29], v[170:173], v[208:211], v[26:29]
	v_mfma_f32_16x16x32_bf16 v[18:21], v[180:183], v[208:211], v[18:21]
	v_mfma_f32_16x16x32_bf16 v[10:13], v[170:173], v[216:219], v[10:13]
	v_mfma_f32_16x16x32_bf16 v[2:5], v[180:183], v[216:219], v[2:5]
	v_mfma_f32_16x16x32_bf16 v[58:61], v[174:177], v[196:199], v[58:61]
	v_mfma_f32_16x16x32_bf16 v[50:53], v[184:187], v[196:199], v[50:53]
	v_mfma_f32_16x16x32_bf16 v[42:45], v[174:177], v[204:207], v[42:45]
	v_mfma_f32_16x16x32_bf16 v[34:37], v[184:187], v[204:207], v[34:37]
	v_mfma_f32_16x16x32_bf16 v[26:29], v[174:177], v[212:215], v[26:29]
	v_mfma_f32_16x16x32_bf16 v[18:21], v[184:187], v[212:215], v[18:21]
	v_mfma_f32_16x16x32_bf16 v[10:13], v[174:177], v[220:223], v[10:13]
	v_mfma_f32_16x16x32_bf16 v[2:5], v[184:187], v[220:223], v[2:5]
	s_setprio 0
	s_barrier
	s_add_i32 s76, s76, 2
	s_add_u32 s48, s48, 0x10000
	s_addc_u32 s49, s49, 0
	s_add_u32 s68, s68, 0x10000
	s_addc_u32 s69, s69, 0
	s_cmp_gt_u32 s76, 61
	s_cbranch_scc0 .LBB0_115
	s_and_b64 vcc, exec, s[14:15]
	s_cbranch_vccz .LBB0_118
	s_barrier
